# c12: last in-proj tile round split in halves across all workgroups
# baseline (speedup 1.0000x reference)
; #define LDSAS __attribute__((address_space(3)))
; #define G_ISSUE(kt, st) do { G_ISSUE1(kt, st, 0); G_ISSUE1(kt, st, 1); G_ISSUE1(kt, st, 2); G_ISSUE1(kt, st, 3); } while (0)
; template <bool LOWREG = false>
; __device__ __forceinline__ void gemm_core(const bf16_t* __restrict__ A, int lda, const bf16_t* __restrict__ Bt, int ldb, int K, f32x4 (&acc)[8][4], unsigned char* smem, int tid) {
;     asm volatile("" : "+v"(tid));
;     const int lane = tid & 63, w = __builtin_amdgcn_readfirstlane(tid >> 6), wm = w >> 2, wn = w & 3, idx = lane & 15, kq = lane >> 4;
;     unsigned offA[4], offB[4];
; #pragma unroll
;     for (int j = 0; j < 4; ++j) { const int row = (j * 8 + w) * 8 + (lane >> 3), c = (lane & 7) ^ ((row >> 1) & 7);
;         offA[j] = (unsigned)(row * lda + c * 8) * 2u; offB[j] = (unsigned)(row * ldb + c * 8) * 2u; }
; #pragma unroll
;     for (int mi = 0; mi < 8; ++mi)
; #pragma unroll
;         for (int ni = 0; ni < 4; ++ni) acc[mi][ni] = (f32x4){0.f, 0.f, 0.f, 0.f};
;     LDSAS unsigned char* lds = (LDSAS unsigned char*)smem;
;     ...
;     const int nk = K >> 6;
;     G_ISSUE(0, 0);
;     asm volatile("s_waitcnt vmcnt(0)" ::: "memory");
;     __syncthreads();
;     const int swz = (idx >> 1) & 7;
;     const int aoff = (wm * 128 + idx) * 128, boff = G_AB + (wn * 64 + idx) * 128;
; __device__ void gemm1_phase(const Params& p, int l, int hb, unsigned char* smem) {
;     ...
;     for (int t = blockIdx.x; t < NTILES; t += gridDim.x) {
;         const int grp = t / GRP, r = t % GRP, jx = NT * (r & 7) + (r >> 3), mt = grp * 8 + (jx & 7), nt = jx >> 3;
;         const int m0 = mt * 256, n0 = nt * 256;
;         f32x4 acc[8][4];
;         int tid = threadIdx.x;
;         gemm_core(H + (size_t)m0 * 1024, 1024, Wt + (size_t)n0 * 1024, 1024, 1024, acc, smem, tid);
.LBB0_253:
	s_add_i32 s60, s60, s8
	s_cmpk_lt_i32 s60, 0x900
	s_waitcnt lgkmcnt(0)
	s_barrier
	s_cbranch_scc0 .LBB0_572
.LBB0_254:
	s_mov_b32 s99, s60
	s_mov_b32 s100, -1
	s_cmpk_lt_i32 s60, 0x800
	s_cbranch_scc1 .Lg1_nosplit
	s_sub_i32 s99, s60, 0x800
	s_and_b32 s100, s99, 1
	s_lshr_b32 s99, s99, 1
	s_addk_i32 s99, 0x800
.Lg1_nosplit:
	s_mul_hi_i32 s9, s99, 0x78787879
	s_lshr_b32 s11, s9, 31
	s_ashr_i32 s9, s9, 7
	s_add_i32 s9, s9, s11
	s_mul_i32 s11, s9, 0x110
	s_sub_i32 s11, s99, s11
	s_and_b32 s12, s11, 7
	s_mul_i32 s12, s12, 34
	s_ashr_i32 s11, s11, 3
	s_add_i32 s12, s12, s11
	s_lshl_b32 s11, s12, 8
	s_lshl_b32 s9, s9, 11
	s_and_b32 s11, s11, 0x700
	s_or_b32 s56, s11, s9
	s_lshl_b32 s11, s12, 5
	s_ashr_i32 s57, s56, 31
	s_and_b32 s36, s11, 0xffffff00
	s_lshl_b64 s[16:17], s[56:57], 11
	s_add_u32 s18, s92, s16
	s_addc_u32 s19, s93, s17
	s_ashr_i32 s37, s36, 31
	s_lshl_b64 s[20:21], s[36:37], 11
	v_mov_b32_e32 v0, v210
	s_add_u32 s22, s94, s20
	s_addc_u32 s23, s95, s21
	v_readfirstlane_b32 s12, v0
	s_ashr_i32 s24, s12, 6
	s_and_b32 s101, s24, 3
	s_cmp_lg_u32 s101, 0
	s_cselect_b32 s101, 1, 0
	s_cmp_eq_u32 s36, 0x2100
	s_cselect_b32 s101, s101, 0
	s_lshr_b32 s98, s24, 2
	s_cmp_lg_u32 s98, s100
	s_cselect_b32 s98, 1, 0
	s_cmp_lt_i32 s100, 0
	s_cselect_b32 s98, 0, s98
	s_or_b32 s101, s101, s98
	v_bfe_u32 v2, v0, 3, 3
	v_lshl_or_b32 v3, s24, 3, v2
	v_lshrrev_b32_e32 v4, 1, v3
	v_xor_b32_e32 v4, v4, v0
	v_lshlrev_b32_e32 v4, 4, v4
	s_lshl_b32 s9, s24, 10
	v_and_b32_e32 v4, 0x70, v4
	s_add_i32 s9, s9, 0
	v_lshl_or_b32 v3, v3, 11, v4
	s_mov_b32 m0, s9
	v_add_u32_e32 v5, 0x20000, v3
	global_load_lds_dwordx4 v3, s[18:19]
	s_add_i32 m0, s9, 0x8000
	v_add_u32_e32 v6, 0x40000, v3
	global_load_lds_dwordx4 v3, s[22:23]
	s_add_i32 m0, s9, 0x2000
	v_add_u32_e32 v7, 0x60000, v3
	global_load_lds_dwordx4 v5, s[18:19]
	s_add_i32 m0, s9, 0xa000
	v_and_b32_e32 v1, 15, v0
	global_load_lds_dwordx4 v5, s[22:23]
	s_add_i32 m0, s9, 0x4000
	v_bfe_u32 v8, v0, 4, 2
	global_load_lds_dwordx4 v6, s[18:19]
	s_add_i32 m0, s9, 0xc000
	v_lshrrev_b32_e32 v3, 1, v0
	global_load_lds_dwordx4 v6, s[22:23]
	s_add_i32 m0, s9, 0x6000
	v_bfe_u32 v0, v0, 1, 3
	global_load_lds_dwordx4 v7, s[18:19]
	s_add_i32 m0, s9, 0xe000
	s_lshr_b32 s18, s12, 1
	global_load_lds_dwordx4 v7, s[22:23]
	s_and_b32 s18, s18, 0x1ffff80
	s_and_b32 s12, s12, 0xc0
	v_or_b32_e32 v5, s18, v1
	v_or_b32_e32 v1, s12, v1
	s_lshl_b32 s12, s24, 14
	s_add_u32 s16, s96, s16
	v_lshlrev_b32_e32 v149, 7, v5
	v_bitop3_b32 v0, v8, v0, 4 bitop3:0x36
	v_lshlrev_b32_e32 v5, 11, v2
	s_addc_u32 s17, s97, s17
	s_add_i32 s18, s12, 0x20000
	v_lshlrev_b32_e32 v147, 7, v1
	v_bitop3_b32 v1, v8, v3, 7 bitop3:0x78
	v_lshlrev_b32_e32 v146, 4, v0
	v_or3_b32 v80, s12, v5, v4
	v_or3_b32 v0, s18, v5, v4
	s_add_i32 s18, s12, 0x40000
	s_add_i32 s12, s12, 0x60000
	v_lshlrev_b32_e32 v148, 4, v1
	v_mov_b32_e32 v1, v81
	v_or3_b32 v2, s18, v5, v4
	v_mov_b32_e32 v3, v81
	v_or3_b32 v4, s12, v5, v4
	v_mov_b32_e32 v5, v81
	v_lshl_add_u64 v[130:131], s[16:17], 0, v[80:81]
	v_lshl_add_u64 v[132:133], s[16:17], 0, v[0:1]
	v_lshl_add_u64 v[134:135], s[16:17], 0, v[2:3]
	v_lshl_add_u64 v[136:137], s[16:17], 0, v[4:5]
	s_add_u32 s16, s64, s20
	s_waitcnt vmcnt(0)
	s_addc_u32 s17, s65, s21
	v_lshl_add_u64 v[140:141], s[16:17], 0, v[0:1]
	v_mov_b32_e32 v0, 0
	v_lshl_add_u64 v[138:139], s[16:17], 0, v[80:81]
	v_lshl_add_u64 v[142:143], s[16:17], 0, v[2:3]
	v_lshl_add_u64 v[144:145], s[16:17], 0, v[4:5]
	s_mov_b32 s12, 0
	s_mov_b64 s[38:39], 0
	v_mov_b32_e32 v1, v0
	v_mov_b32_e32 v2, v0
	v_mov_b32_e32 v3, v0
	v_mov_b32_e32 v4, v0
	v_mov_b32_e32 v5, v0
	v_mov_b32_e32 v6, v0
	v_mov_b32_e32 v7, v0
	v_mov_b32_e32 v8, v0
	v_mov_b32_e32 v9, v0
	s_waitcnt vmcnt(0)
	v_mov_b32_e32 v10, v0
	v_mov_b32_e32 v11, v0
	v_mov_b32_e32 v12, v0
	v_mov_b32_e32 v13, v0
	v_mov_b32_e32 v14, v0
	v_mov_b32_e32 v15, v0
	v_mov_b32_e32 v16, v0
	v_mov_b32_e32 v17, v0
	v_mov_b32_e32 v18, v0
	v_mov_b32_e32 v19, v0
	v_mov_b32_e32 v20, v0
	v_mov_b32_e32 v21, v0
	v_mov_b32_e32 v22, v0
	v_mov_b32_e32 v23, v0
	v_mov_b32_e32 v24, v0
	v_mov_b32_e32 v25, v0
	v_mov_b32_e32 v26, v0
	v_mov_b32_e32 v27, v0
	v_mov_b32_e32 v28, v0
	v_mov_b32_e32 v29, v0
	v_mov_b32_e32 v30, v0
	v_mov_b32_e32 v31, v0
	v_mov_b32_e32 v32, v0
	v_mov_b32_e32 v33, v0
	v_mov_b32_e32 v34, v0
	v_mov_b32_e32 v35, v0
	v_mov_b32_e32 v36, v0
	v_mov_b32_e32 v37, v0
	v_mov_b32_e32 v38, v0
	v_mov_b32_e32 v39, v0
	v_mov_b32_e32 v40, v0
	v_mov_b32_e32 v41, v0
	v_mov_b32_e32 v42, v0
	v_mov_b32_e32 v43, v0
	v_mov_b32_e32 v44, v0
	v_mov_b32_e32 v45, v0
	v_mov_b32_e32 v46, v0
	v_mov_b32_e32 v47, v0
	v_mov_b32_e32 v48, v0
	v_mov_b32_e32 v49, v0
	v_mov_b32_e32 v50, v0
	v_mov_b32_e32 v51, v0
	v_mov_b32_e32 v52, v0
	v_mov_b32_e32 v53, v0
	v_mov_b32_e32 v54, v0
	v_mov_b32_e32 v55, v0
	v_mov_b32_e32 v56, v0
	v_mov_b32_e32 v57, v0
	v_mov_b32_e32 v58, v0
	v_mov_b32_e32 v59, v0
	v_mov_b32_e32 v60, v0
	v_mov_b32_e32 v61, v0
	v_mov_b32_e32 v62, v0
	v_mov_b32_e32 v63, v0
	v_mov_b32_e32 v64, v0
	v_mov_b32_e32 v65, v0
	v_mov_b32_e32 v66, v0
	v_mov_b32_e32 v67, v0
	v_mov_b32_e32 v68, v0
	v_mov_b32_e32 v69, v0
	v_mov_b32_e32 v70, v0
	v_mov_b32_e32 v71, v0
	v_mov_b32_e32 v72, v0
	v_mov_b32_e32 v73, v0
	v_mov_b32_e32 v74, v0
	v_mov_b32_e32 v75, v0
	v_mov_b32_e32 v76, v0
	v_mov_b32_e32 v77, v0
	v_mov_b32_e32 v78, v0
	v_mov_b32_e32 v79, v0
	v_mov_b32_e32 v82, v0
	v_mov_b32_e32 v83, v0
	v_mov_b32_e32 v84, v0
	v_mov_b32_e32 v85, v0
	v_mov_b32_e32 v86, v0
	v_mov_b32_e32 v87, v0
	v_mov_b32_e32 v88, v0
	v_mov_b32_e32 v89, v0
	v_mov_b32_e32 v90, v0
	v_mov_b32_e32 v91, v0
	v_mov_b32_e32 v92, v0
	v_mov_b32_e32 v93, v0
	v_mov_b32_e32 v94, v0
	v_mov_b32_e32 v95, v0
	v_mov_b32_e32 v96, v0
	v_mov_b32_e32 v97, v0
	v_mov_b32_e32 v98, v0
	v_mov_b32_e32 v99, v0
	v_mov_b32_e32 v100, v0
	v_mov_b32_e32 v101, v0
	v_mov_b32_e32 v102, v0
	v_mov_b32_e32 v103, v0
	v_mov_b32_e32 v104, v0
	v_mov_b32_e32 v105, v0
	v_mov_b32_e32 v106, v0
	v_mov_b32_e32 v107, v0
	v_mov_b32_e32 v108, v0
	v_mov_b32_e32 v109, v0
	v_mov_b32_e32 v110, v0
	v_mov_b32_e32 v111, v0
	v_mov_b32_e32 v112, v0
	v_mov_b32_e32 v113, v0
	v_mov_b32_e32 v114, v0
	v_mov_b32_e32 v115, v0
	v_mov_b32_e32 v116, v0
	v_mov_b32_e32 v117, v0
	v_mov_b32_e32 v118, v0
	v_mov_b32_e32 v119, v0
	v_mov_b32_e32 v120, v0
	v_mov_b32_e32 v121, v0
	v_mov_b32_e32 v122, v0
	v_mov_b32_e32 v123, v0
	v_mov_b32_e32 v124, v0
	v_mov_b32_e32 v125, v0
	v_mov_b32_e32 v126, v0
	v_mov_b32_e32 v127, v0
	v_mov_b32_e32 v128, v0
	v_mov_b32_e32 v129, v0
	s_waitcnt lgkmcnt(0)
	s_barrier

; __device__ void gemm1_phase(const Params& p, int l, int hb, unsigned char* smem) {
;     ...
;         gemm_core(H + (size_t)m0 * 1024, 1024, Wt + (size_t)n0 * 1024, 1024, 1024, acc, smem, tid);
;         asm volatile("" : "+v"(tid));
;         const int lane = tid & 63, w = __builtin_amdgcn_readfirstlane(tid >> 6), wm = w >> 2, wn = w & 3, idx = lane & 15, kq = lane >> 4;
;         const int cw = n0 + wn * 64;
;         const int lc = 4 * kq;
;         unsigned char* wl = smem + w * 16384;
.Lg1_dtskip4:
	s_waitcnt lgkmcnt(0)
	v_mov_b32_e32 v181, v210
	s_waitcnt vmcnt(0)
	s_barrier
	s_cmp_lg_u32 s98, 0
	s_cbranch_scc1 .LBB0_253
	s_nop 0
	v_readfirstlane_b32 s9, v181
	s_ashr_i32 s57, s9, 8
	s_and_b32 s55, s9, 0xc0
	s_lshl_b32 s9, s9, 8
	s_and_b32 s9, s9, 0xffffc000
	v_bfe_u32 v156, v181, 4, 2
	s_or_b32 s54, s55, s36
	s_add_i32 s61, s9, 0
	v_and_b32_e32 v230, 63, v181
	v_and_b32_e32 v231, 15, v181
	v_lshlrev_b32_e32 v157, 2, v156
	s_cmpk_gt_i32 s54, 0x27f
	s_mov_b64 s[36:37], -1
	s_cbranch_scc1 .LBB0_259
	s_andn2_b64 vcc, exec, s[36:37]
	v_and_b32_e32 v179, 7, v181
	s_cbranch_vccz .LBB0_521
